# stage Y: static priority raise (s_setprio 2) for waves 0-3, the longer group there; dropped before the closing barrier
# baseline (speedup 1.0000x reference)
.Lpq0_end:
	s_waitcnt lgkmcnt(0)
	s_barrier
	s_and_b64 s[98:99], s[54:55], exec
	s_cbranch_scc0 .Lyp0a
	s_setprio 2
.Lyp0a:
	ds_read_b128 v[48:51], v180
	ds_read_b128 v[52:55], v241 offset:62976
	ds_read_b128 v[56:59], v241 offset:64256
	ds_read_b128 v[88:91], v242
	ds_read_b128 v[92:95], v242 offset:64
	s_and_b64 s[98:99], s[56:57], exec
	s_cbranch_scc0 .Lcp0
	s_cmp_gt_u32 s36, 62
	s_cbranch_scc1 .Lcp0
	s_cmp_eq_u32 s36, 0
	s_cbranch_scc1 .Lvw0
	s_waitcnt vmcnt(16)
	s_branch .Lvx0

.LBB0_424:
.LBB0_426:
	s_and_b64 s[98:99], s[54:55], exec
	s_cbranch_scc0 .Lyp0b
	s_setprio 0
.Lyp0b:
	s_add_i32 s24, s19, -16
	s_and_b64 s[2:3], s[12:13], exec
	s_waitcnt lgkmcnt(0)
	s_barrier
	s_cselect_b32 s2, s21, s24
	s_cmpk_lt_u32 s20, 0x7f
	ds_read_b64 v[236:237], v190
	ds_read_b64 v[234:235], v244
	v_lshl_add_u32 v194, s2, 6, v183
	s_cselect_b64 s[2:3], -1, 0
	v_lshl_add_u64 v[238:239], v[194:195], 1, s[78:79]
	s_and_b64 s[68:69], s[54:55], s[2:3]

.Lyp1a:
	s_and_b64 s[24:25], s[46:47], s[2:3]
	ds_read_b128 v[48:51], v180 offset:5120
	ds_read_b128 v[52:55], v170 offset:5120
	ds_read_b128 v[56:59], v170 offset:6400
	ds_read_b128 v[88:91], v242 offset:256
	ds_read_b128 v[92:95], v242 offset:320
	s_and_b64 s[98:99], s[56:57], exec
	s_cbranch_scc0 .Lcp1
	s_cmp_gt_u32 s36, 62
	s_cbranch_scc1 .Lcp1
	s_cmp_eq_u32 s36, 0
	s_cbranch_scc1 .Lvw1
	s_cmp_gt_u32 s36, 61
	s_cbranch_scc1 .Lvw1
	s_waitcnt vmcnt(16)
	s_branch .Lvx1

.LBB0_453:
	s_and_b64 s[98:99], s[54:55], exec
	s_cbranch_scc0 .Lyp1b
	s_setprio 0
